# stack: division simplification + out-norm gains hoist + first-segment ds_read hoist
# speedup vs baseline: 1.0031x; 1.0007x over previous
;     __host__ __device__ bool next(int i, Unit& u) const {
;         const long L = (long)i * G + c; if (L >= nwg) return false;
;         int wgid = (int)L; { const int q = nwg / NXCD, r = nwg % NXCD, xcd = wgid % NXCD, off = wgid / NXCD; wgid = (xcd < r ? xcd * (q + 1) : r * (q + 1) + (xcd - r) * q) + off; }
;         const int nig = WGM * nN, gid = wgid / nig, fm = gid * WGM, gsz = (nM - fm) < WGM ? (nM - fm) : WGM;
;         u.pm = fm + ((wgid % nig) % gsz); u.pn = (wgid % nig) / gsz; u.idx = i; return true;
.LBB0_604:
	ds_read_b128 v[154:157], v148
	ds_read_b128 v[158:161], v148 offset:1024
	ds_read_b128 v[162:165], v148 offset:2048
	ds_read_b128 v[166:169], v148 offset:3072
	ds_read_b128 v[170:173], v149
	ds_read_b128 v[174:177], v149 offset:1024
	ds_read_b128 v[178:181], v149 offset:2048
	ds_read_b128 v[182:185], v149 offset:3072
	ds_read_b128 v[186:189], v150
	ds_read_b128 v[190:193], v150 offset:1024
	ds_read_b128 v[194:197], v150 offset:2048
	ds_read_b128 v[198:201], v150 offset:3072
	ds_read_b128 v[202:205], v150 offset:4096
	ds_read_b128 v[206:209], v150 offset:5120
	ds_read_b128 v[210:213], v150 offset:6144
	ds_read_b128 v[214:217], v150 offset:7168
	s_add_i32 s43, s43, 1
	s_mul_i32 s2, s43, s0
	s_mul_hi_u32 s3, s43, s76
	s_add_i32 s3, s3, s2
	s_mul_i32 s2, s43, s76
	s_add_u32 s16, s2, s97
	s_addc_u32 s17, s3, s1
	v_cmp_gt_i64_e32 vcc, s[16:17], v[142:143]
	v_cmp_lt_i64_e64 s[2:3], s[16:17], v[140:141]
	s_cbranch_vccnz .LBB0_606
	s_ashr_i32 s12, s16, 31
	s_lshr_b32 s12, s12, 29
	s_add_i32 s12, s16, s12
	s_ashr_i32 s13, s12, 3
	s_and_b32 s12, s12, -8
	s_sub_i32 s12, s16, s12
	s_cmp_lt_i32 s12, 0
	s_cselect_b32 s14, s34, 0x160
	s_mul_i32 s12, s12, s14
	s_add_i32 s12, s12, s13
	s_mul_hi_i32 s13, s12, 0x2e8ba2e9
	s_lshr_b32 s14, s13, 31
	s_ashr_i32 s13, s13, 4
	s_add_i32 s13, s13, s14
	s_lshl_b32 s14, s13, 2
	s_mulk_i32 s13, 0x58
	s_sub_i32 s13, s12, s13
	s_abs_i32 s12, s13
	s_mov_b32 s44, s43
	s_lshr_b32 s12, s13, 2
	s_and_b32 s13, s13, 3
	s_add_i32 s14, s14, s13

;     __host__ __device__ bool next(int i, Unit& u) const {
;         const long L = (long)i * G + c; if (L >= nwg) return false;
;         int wgid = (int)L; { const int q = nwg / NXCD, r = nwg % NXCD, xcd = wgid % NXCD, off = wgid / NXCD; wgid = (xcd < r ? xcd * (q + 1) : r * (q + 1) + (xcd - r) * q) + off; }
;         const int nig = WGM * nN, gid = wgid / nig, fm = gid * WGM, gsz = (nM - fm) < WGM ? (nM - fm) : WGM;
;         u.pm = fm + ((wgid % nig) % gsz); u.pn = (wgid % nig) / gsz; u.idx = i; return true;
.LBB0_871:
	ds_read_b128 v[146:149], v158
	ds_read_b128 v[162:165], v158 offset:1024
	ds_read_b128 v[166:169], v158 offset:2048
	ds_read_b128 v[170:173], v158 offset:3072
	ds_read_b128 v[174:177], v159
	ds_read_b128 v[178:181], v159 offset:1024
	ds_read_b128 v[182:185], v159 offset:2048
	ds_read_b128 v[186:189], v159 offset:3072
	ds_read_b128 v[190:193], v160
	ds_read_b128 v[194:197], v160 offset:1024
	ds_read_b128 v[198:201], v160 offset:2048
	ds_read_b128 v[202:205], v160 offset:3072
	ds_read_b128 v[206:209], v160 offset:4096
	ds_read_b128 v[210:213], v160 offset:5120
	ds_read_b128 v[214:217], v160 offset:6144
	ds_read_b128 v[218:221], v160 offset:7168
	s_add_i32 s48, s48, 1
	s_mul_i32 s4, s48, s0
	s_mul_hi_u32 s5, s48, s76
	s_add_i32 s5, s5, s4
	s_mul_i32 s4, s48, s76
	s_add_u32 s22, s4, s97
	s_addc_u32 s23, s5, s1
	v_cmp_gt_i64_e32 vcc, s[22:23], v[144:145]
	v_cmp_lt_i64_e64 s[4:5], s[22:23], v[142:143]
	s_cbranch_vccnz .LBB0_873
	s_ashr_i32 s18, s22, 31
	s_lshr_b32 s18, s18, 29
	s_add_i32 s18, s22, s18
	s_ashr_i32 s19, s18, 3
	s_and_b32 s18, s18, -8
	s_sub_i32 s18, s22, s18
	s_cmp_lt_i32 s18, 0
	s_cselect_b32 s20, s43, 0x120
	s_mul_i32 s18, s18, s20
	s_add_i32 s18, s18, s19
	s_mul_hi_i32 s19, s18, 0x38e38e39
	s_lshr_b32 s20, s19, 31
	s_ashr_i32 s19, s19, 4
	s_add_i32 s19, s19, s20
	s_lshl_b32 s20, s19, 2
	s_mulk_i32 s19, 0x48
	s_sub_i32 s19, s18, s19
	s_abs_i32 s18, s19
	s_mov_b32 s49, s48
	s_lshr_b32 s18, s19, 2
	s_and_b32 s19, s19, 3
	s_add_i32 s20, s20, s19

;     __host__ __device__ bool next(int i, Unit& u) const {
;         const long L = (long)i * G + c; if (L >= nwg) return false;
;         int wgid = (int)L; { const int q = nwg / NXCD, r = nwg % NXCD, xcd = wgid % NXCD, off = wgid / NXCD; wgid = (xcd < r ? xcd * (q + 1) : r * (q + 1) + (xcd - r) * q) + off; }
;         const int nig = WGM * nN, gid = wgid / nig, fm = gid * WGM, gsz = (nM - fm) < WGM ? (nM - fm) : WGM;
;         u.pm = fm + ((wgid % nig) % gsz); u.pn = (wgid % nig) / gsz; u.idx = i; return true;
.LBB0_1610:
	ds_read_b128 v[154:157], v148
	ds_read_b128 v[158:161], v148 offset:1024
	ds_read_b128 v[162:165], v148 offset:2048
	ds_read_b128 v[166:169], v148 offset:3072
	ds_read_b128 v[170:173], v149
	ds_read_b128 v[174:177], v149 offset:1024
	ds_read_b128 v[178:181], v149 offset:2048
	ds_read_b128 v[182:185], v149 offset:3072
	ds_read_b128 v[186:189], v150
	ds_read_b128 v[190:193], v150 offset:1024
	ds_read_b128 v[194:197], v150 offset:2048
	ds_read_b128 v[198:201], v150 offset:3072
	ds_read_b128 v[202:205], v150 offset:4096
	ds_read_b128 v[206:209], v150 offset:5120
	ds_read_b128 v[210:213], v150 offset:6144
	ds_read_b128 v[214:217], v150 offset:7168
	s_add_i32 s41, s41, 1
	s_mul_i32 s2, s41, s0
	s_mul_hi_u32 s3, s41, s76
	s_add_i32 s3, s3, s2
	s_mul_i32 s2, s41, s76
	s_add_u32 s14, s2, s97
	s_addc_u32 s15, s3, s1
	v_cmp_gt_i64_e32 vcc, s[14:15], v[142:143]
	v_cmp_lt_i64_e64 s[2:3], s[14:15], v[140:141]
	s_cbranch_vccnz .LBB0_1612
	s_ashr_i32 s10, s14, 31
	s_lshr_b32 s10, s10, 29
	s_add_i32 s10, s14, s10
	s_ashr_i32 s11, s10, 3
	s_and_b32 s10, s10, -8
	s_sub_i32 s10, s14, s10
	s_cmp_lt_i32 s10, 0
	s_cselect_b32 s12, s31, 0x160
	s_mul_i32 s10, s10, s12
	s_add_i32 s10, s10, s11
	s_mul_hi_i32 s11, s10, 0x2e8ba2e9
	s_lshr_b32 s12, s11, 31
	s_ashr_i32 s11, s11, 4
	s_add_i32 s11, s11, s12
	s_lshl_b32 s12, s11, 2
	s_mulk_i32 s11, 0x58
	s_sub_i32 s11, s10, s11
	s_abs_i32 s10, s11
	s_mov_b32 s42, s41
	s_lshr_b32 s10, s11, 2
	s_and_b32 s11, s11, 3
	s_add_i32 s12, s12, s11
